# v139 plus a warm-up touch of the out-projection epilogue's residual (x for layer 0, HB for layer 1) at the phase entry
# baseline (speedup 1.0000x reference)
.LBB0_89:
	v_readlane_b32 s0, v255, 16
	s_cmp_lt_i32 s0, 5
	s_mov_b64 s[4:5], -1
	s_cbranch_scc1 .LBB0_171
	v_readlane_b32 s0, v255, 16
	s_cmp_eq_u32 s0, 5
	s_cbranch_scc0 .LBB0_170
	s_cmp_lg_u32 s94, 5
	s_cbranch_scc1 .Lwarm_res_hb
	s_load_dwordx2 s[0:1], s[70:71], 0x0
	v_lshl_add_u32 v252, s80, 9, v235
	v_lshlrev_b32_e32 v252, 7, v252
	s_waitcnt lgkmcnt(0)
	global_load_dword v253, v252, s[0:1]
	s_add_u32 s0, s0, 0x1000000
	s_addc_u32 s1, s1, 0
	global_load_dword v253, v252, s[0:1]
	s_add_u32 s0, s0, 0x1000000
	s_addc_u32 s1, s1, 0
	global_load_dword v253, v252, s[0:1]
	s_add_u32 s0, s0, 0x1000000
	s_addc_u32 s1, s1, 0
	global_load_dword v253, v252, s[0:1]
	s_branch .Lwarm_res_done
.Lwarm_res_hb:
	s_add_u32 s0, s12, 0x8400000
	s_addc_u32 s1, s13, 0
	v_lshl_add_u32 v252, s80, 9, v235
	v_lshlrev_b32_e32 v252, 7, v252
	global_load_dword v253, v252, s[0:1]
	s_add_u32 s0, s0, 0x1000000
	s_addc_u32 s1, s1, 0
	global_load_dword v253, v252, s[0:1]
.Lwarm_res_done:
	v_lshl_add_u32 v246, s80, 9, v235
	v_lshlrev_b32_e32 v246, 7, v246
	v_add_u32_e32 v248, 0x3400000, v246
	v_add_u32_e32 v246, 0x2400000, v246
	v_mov_b32_e32 v247, 0
	v_mov_b32_e32 v249, 0
	v_lshl_add_u64 v[246:247], s[12:13], 0, v[246:247]
	v_lshl_add_u64 v[248:249], s[12:13], 0, v[248:249]
	global_load_dword v250, v[246:247], off
	global_load_dword v250, v[248:249], off
	s_add_u32 s0, s12, 0x6400000
	s_addc_u32 s1, s13, 0
	s_add_u32 s2, s12, 0x1c00000
	s_addc_u32 s3, s13, 0
	s_add_i32 s4, s94, 8
	s_cmp_gt_u32 s4, 16
	s_mov_b64 s[4:5], -1
	s_cbranch_scc0 .LBB0_131
	s_cmpk_lt_i32 s80, 0x100
	s_cselect_b64 s[18:19], -1, 0
	s_cmpk_gt_i32 s80, 0xff
	v_readfirstlane_b32 s14, v235
	s_cbranch_scc1 .LBB0_98
	s_ashr_i32 s4, s80, 31
	s_lshr_b32 s4, s4, 29
	s_add_i32 s15, s80, s4
	s_and_b32 s4, s15, -8
	s_sub_i32 s21, s80, s4
	s_cmp_gt_i32 s21, -1
	s_mov_b64 s[4:5], -1
	s_cbranch_scc0 .LBB0_95
	s_lshl_b32 s23, s21, 5
	s_mov_b64 s[4:5], 0
